# diff_attn item prologue: 4 Q-fragment loads batched; gate S-matrix: 16 ki/qd loads hoisted with counted waits (stacked on v6)
# speedup vs baseline: 1.0028x; 1.0028x over previous
; #define LAS __attribute__((address_space(3)))
; DI bf16_t f2bf(float x) { return (bf16_t)(pk2(x, 0.f) & 0xffffu); }
; DI float bf2f(bf16_t v) { return __uint_as_float(((unsigned)v) << 16); }
; DI float logsig(float z) { return fminf(z, 0.f) - __logf(1.f + __expf(-fabsf(z))); }
; DI void gla_gate_phase(int wv, LAS unsigned char* lds, const float* x, const float* w_in, const float* w2, const float* bg, const bf16_t* qk1,
;                        bf16_t* qd, bf16_t* ki, bf16_t* kst, float* decay, bf16_t* sbuf) {
;     ...
;         for (int t8 = 0; t8 < 64; t8 += 8) {
;             float ksv[8];
; #pragma unroll
;             for (int u = 0; u < 8; ++u) { const int t = t8 + u; float z = bc;
; #pragma unroll
;                 for (int q = 0; q < 4; ++q) { const f32x4 gv = *(const LAS f32x4*)(gl + t * 16 + 4 * q); z += gv.x * w2c[4 * q] + gv.y * w2c[4 * q + 1] + gv.z * w2c[4 * q + 2] + gv.w * w2c[4 * q + 3]; }
;                 cum += logsig(z) * 0.0625f;
;                 const size_t tok = T0 + t;
;                 const float qv = bf2f(qk1[tok * 1024 + c]), kv = bf2f(qk1[tok * 1024 + 512 + c]);
;                 qd[tok * 512 + c] = f2bf(qv * 0.08838834764831845f * __expf(cum));
;                 ki[tok * 512 + c] = f2bf(kv * __expf(-cum));
;                 ksv[u] = kv * __expf(blast - cum); }
.LBB0_148:
	v_lshl_add_u64 v[200:201], s[48:49], 0, v[6:7]
	v_mov_b32_e32 v204, 0x1000
	v_mov_b32_e32 v205, 0
	v_mov_b32_e32 v206, 0x3000
	v_mov_b32_e32 v207, 0
	v_lshl_add_u64 v[202:203], v[204:205], 0, v[200:201]
	v_lshl_add_u64 v[208:209], v[206:207], 0, v[200:201]
	global_load_ushort v210, v[202:203], off offset:-4096
	global_load_ushort v211, v[202:203], off offset:-3072
	global_load_ushort v212, v[202:203], off offset:-2048
	global_load_ushort v213, v[202:203], off offset:-1024
	global_load_ushort v214, v[202:203], off
	global_load_ushort v215, v[202:203], off offset:1024
	global_load_ushort v216, v[202:203], off offset:2048
	global_load_ushort v217, v[202:203], off offset:3072
	global_load_ushort v218, v[208:209], off offset:-4096
	global_load_ushort v219, v[208:209], off offset:-3072
	global_load_ushort v220, v[208:209], off offset:-2048
	global_load_ushort v221, v[208:209], off offset:-1024
	global_load_ushort v222, v[208:209], off
	global_load_ushort v223, v[208:209], off offset:1024
	global_load_ushort v224, v[208:209], off offset:2048
	global_load_ushort v225, v[208:209], off offset:3072
	v_mov_b32_e32 v106, s6
	ds_read_b128 v[2:5], v106
	ds_read_b128 v[96:99], v106 offset:16
	ds_read_b128 v[100:103], v106 offset:32
	ds_read_b128 v[108:111], v106 offset:48
	s_brev_b32 s2, 32
	s_waitcnt lgkmcnt(3)
	v_mov_b32_e32 v104, v2
	s_waitcnt lgkmcnt(2)
	v_mov_b32_e32 v105, v96
	v_mov_b32_e32 v96, v3
	v_pk_mul_f32 v[2:3], v[22:23], v[96:97]
	v_mov_b32_e32 v96, v4
	v_pk_fma_f32 v[2:3], v[20:21], v[104:105], v[2:3]
	v_mov_b32_e32 v97, v98
	v_pk_fma_f32 v[2:3], v[24:25], v[96:97], v[2:3]
	v_mov_b32_e32 v98, v5
	v_pk_fma_f32 v[2:3], v[26:27], v[98:99], v[2:3]
	s_add_i32 s1, s1, 8
	v_add_f32_e32 v2, v37, v2
	v_add_f32_e32 v96, v2, v3
	s_waitcnt lgkmcnt(0)
	v_mov_b32_e32 v3, v108
	v_mov_b32_e32 v108, v101
	v_mov_b32_e32 v2, v100
	v_pk_mul_f32 v[4:5], v[30:31], v[108:109]
	s_addk_i32 s6, 0x200
	v_pk_fma_f32 v[2:3], v[28:29], v[2:3], v[4:5]
	v_mov_b32_e32 v4, v102
	v_mov_b32_e32 v5, v110
	v_pk_fma_f32 v[2:3], v[32:33], v[4:5], v[2:3]
	v_mov_b32_e32 v110, v103
	v_pk_fma_f32 v[2:3], v[34:35], v[110:111], v[2:3]
	v_lshl_add_u64 v[102:103], s[48:49], 0, v[8:9]
	v_add_f32_e32 v2, v96, v2
	v_add_f32_e32 v2, v2, v3
	v_min_f32_e32 v3, 0, v2
	v_mul_f32_e64 v2, |v2|, s89
	v_exp_f32_e32 v2, v2
	v_lshl_add_u64 v[8:9], v[8:9], 0, s[62:63]
	s_cmp_gt_u32 s1, 55
	v_add_f32_e32 v2, 1.0, v2
	v_cmp_gt_f32_e32 vcc, s90, v2
	s_nop 1
	v_cndmask_b32_e64 v4, 0, 32, vcc
	v_ldexp_f32 v2, v2, v4
	v_log_f32_e32 v2, v2
	s_nop 0
	v_mul_f32_e32 v4, 0x3f317217, v2
	v_fma_f32 v4, v2, s91, -v4
	v_fmac_f32_e32 v4, 0x3377d1cf, v2
	v_fmac_f32_e32 v4, 0x3f317217, v2
	v_cmp_lt_f32_e64 s[44:45], |v2|, s92
	s_nop 1
	v_cndmask_b32_e64 v2, v2, v4, s[44:45]
	v_cndmask_b32_e32 v4, 0, v245, vcc
	v_sub_f32_e32 v2, v2, v4
	v_sub_f32_e32 v2, v3, v2
	v_fmac_f32_e32 v95, 0x3d800000, v2
	v_lshl_add_u64 v[2:3], s[48:49], 0, v[6:7]
	s_nop 0
	v_mul_f32_e32 v96, 0x3fb8aa3b, v95
	v_exp_f32_e32 v96, v96
	v_lshl_add_u64 v[6:7], v[6:7], 0, s[64:65]
	s_waitcnt vmcnt(0)
	v_lshlrev_b32_e32 v5, 16, v210
	s_nop 0
	v_mul_f32_e32 v5, 0x3db504f3, v5
	v_mul_f32_e32 v5, v5, v96
	v_cvt_pk_bf16_f32 v5, v5, s0
	v_lshl_add_u64 v[96:97], s[48:49], 0, v[14:15]
	global_store_short v[96:97], v5, off
	ds_read_b128 v[108:111], v106 offset:64
	ds_read_b128 v[112:115], v106 offset:80
	v_mul_f32_e32 v5, 0xbfb8aa3b, v95
	v_exp_f32_e32 v5, v5
	v_sub_f32_e32 v96, v93, v95
	v_mul_f32_e32 v96, 0x3fb8aa3b, v96
	s_waitcnt lgkmcnt(0)
	v_mov_b32_e32 v97, v112
	v_mov_b32_e32 v112, v109
	v_exp_f32_e32 v98, v96
	v_mov_b32_e32 v96, v108
	v_pk_mul_f32 v[100:101], v[22:23], v[112:113]
	v_lshl_add_u64 v[14:15], v[14:15], 0, s[62:63]
	v_pk_fma_f32 v[96:97], v[20:21], v[96:97], v[100:101]
	v_mov_b32_e32 v100, v110
	v_mov_b32_e32 v101, v114
	v_pk_fma_f32 v[96:97], v[24:25], v[100:101], v[96:97]
	v_mov_b32_e32 v114, v111
	v_pk_fma_f32 v[96:97], v[26:27], v[114:115], v[96:97]
	ds_read_b128 v[108:111], v106 offset:96
	ds_read_b128 v[112:115], v106 offset:112
	v_add_f32_e32 v96, v37, v96
	v_add_f32_e32 v99, v96, v97
	s_waitcnt lgkmcnt(1)
	v_mov_b32_e32 v96, v108
	s_waitcnt lgkmcnt(0)
	v_mov_b32_e32 v97, v112
	v_mov_b32_e32 v112, v109
	v_pk_mul_f32 v[100:101], v[30:31], v[112:113]
	s_nop 0
	v_lshlrev_b32_e32 v4, 16, v211
	v_mul_f32_e32 v5, v5, v4
	v_cvt_pk_bf16_f32 v5, v5, s0
	global_store_short v[102:103], v5, off
	s_nop 0
	v_pk_fma_f32 v[96:97], v[28:29], v[96:97], v[100:101]
	v_mov_b32_e32 v100, v110
	v_mov_b32_e32 v101, v114
	v_pk_fma_f32 v[96:97], v[32:33], v[100:101], v[96:97]
	v_mov_b32_e32 v114, v111
	v_pk_fma_f32 v[96:97], v[34:35], v[114:115], v[96:97]
	v_lshl_add_u64 v[100:101], s[48:49], 0, v[10:11]
	v_add_f32_e32 v96, v99, v96
	v_add_f32_e32 v96, v96, v97
	v_min_f32_e32 v97, 0, v96
	v_mul_f32_e64 v96, |v96|, s89
	v_exp_f32_e32 v96, v96
	v_lshl_add_u64 v[10:11], v[10:11], 0, s[62:63]
	v_add_f32_e32 v96, 1.0, v96
	v_cmp_gt_f32_e32 vcc, s90, v96
	s_nop 0
	v_lshlrev_b32_e32 v102, 16, v212
	s_nop 0
	v_cndmask_b32_e64 v99, 0, 32, vcc
	v_ldexp_f32 v96, v96, v99
	v_log_f32_e32 v96, v96
	v_mul_f32_e32 v102, 0x3db504f3, v102
	v_mul_f32_e32 v99, 0x3f317217, v96
	v_fma_f32 v99, v96, s91, -v99
	v_fmac_f32_e32 v99, 0x3377d1cf, v96
	v_fmac_f32_e32 v99, 0x3f317217, v96
	v_cmp_lt_f32_e64 s[44:45], |v96|, s92
	s_nop 0
	v_lshlrev_b32_e32 v5, 16, v213
	v_cndmask_b32_e64 v96, v96, v99, s[44:45]
	v_cndmask_b32_e32 v99, 0, v245, vcc
	v_sub_f32_e32 v96, v96, v99
	v_sub_f32_e32 v96, v97, v96
	v_fmac_f32_e32 v95, 0x3d800000, v96
	v_mul_f32_e32 v96, 0x3fb8aa3b, v95
	v_exp_f32_e32 v104, v96
	v_mul_f32_e32 v96, 0xbfb8aa3b, v95
	v_exp_f32_e32 v105, v96
	v_add_co_u32_e32 v124, vcc, s93, v100
	v_mul_f32_e32 v102, v102, v104
	v_lshl_add_u64 v[96:97], s[48:49], 0, v[12:13]
	v_cvt_pk_bf16_f32 v102, v102, s0
	v_addc_co_u32_e32 v125, vcc, 0, v101, vcc
	v_sub_f32_e32 v99, v93, v95
	global_store_short v[124:125], v102, off offset:1024
	v_mul_f32_e32 v102, v105, v5
	v_add_co_u32_e32 v126, vcc, s2, v96
	v_mul_f32_e32 v99, 0x3fb8aa3b, v99
	v_cvt_pk_bf16_f32 v102, v102, s0
	v_addc_co_u32_e32 v127, vcc, 0, v97, vcc
	v_exp_f32_e32 v99, v99
	global_store_short v[126:127], v102, off offset:1024
	ds_read_b128 v[102:105], v106 offset:128
	ds_read_b128 v[108:111], v106 offset:144
	ds_read_b128 v[112:115], v106 offset:160
	ds_read_b128 v[116:119], v106 offset:176
	s_movk_i32 s2, 0x2000
	v_pk_mul_f32 v[4:5], v[98:99], v[4:5]
	s_waitcnt lgkmcnt(2)
; #define LAS __attribute__((address_space(3)))
; DI bf16_t f2bf(float x) { return (bf16_t)(pk2(x, 0.f) & 0xffffu); }
; DI float bf2f(bf16_t v) { return __uint_as_float(((unsigned)v) << 16); }
; DI float logsig(float z) { return fminf(z, 0.f) - __logf(1.f + __expf(-fabsf(z))); }
; DI void gla_gate_phase(int wv, LAS unsigned char* lds, const float* x, const float* w_in, const float* w2, const float* bg, const bf16_t* qk1,
;                        bf16_t* qd, bf16_t* ki, bf16_t* kst, float* decay, bf16_t* sbuf) {
;     ...
;             for (int u = 0; u < 8; ++u) { const int t = t8 + u; float z = bc;
; #pragma unroll
;                 for (int q = 0; q < 4; ++q) { const f32x4 gv = *(const LAS f32x4*)(gl + t * 16 + 4 * q); z += gv.x * w2c[4 * q] + gv.y * w2c[4 * q + 1] + gv.z * w2c[4 * q + 2] + gv.w * w2c[4 * q + 3]; }
;                 cum += logsig(z) * 0.0625f;
;                 const size_t tok = T0 + t;
;                 const float qv = bf2f(qk1[tok * 1024 + c]), kv = bf2f(qk1[tok * 1024 + 512 + c]);
;                 qd[tok * 512 + c] = f2bf(qv * 0.08838834764831845f * __expf(cum));
;                 ki[tok * 512 + c] = f2bf(kv * __expf(-cum));
;                 ksv[u] = kv * __expf(blast - cum); }
	v_mov_b32_e32 v99, v108
	v_mov_b32_e32 v108, v103
	v_mov_b32_e32 v98, v102
	v_pk_mul_f32 v[102:103], v[22:23], v[108:109]
	v_lshl_add_u64 v[12:13], v[12:13], 0, s[62:63]
	v_pk_fma_f32 v[98:99], v[20:21], v[98:99], v[102:103]
	v_mov_b32_e32 v102, v104
	v_mov_b32_e32 v103, v110
	v_pk_fma_f32 v[98:99], v[24:25], v[102:103], v[98:99]
	v_mov_b32_e32 v110, v105
	v_pk_fma_f32 v[98:99], v[26:27], v[110:111], v[98:99]
	s_nop 0
	v_add_f32_e32 v98, v37, v98
	v_add_f32_e32 v104, v98, v99
	s_waitcnt lgkmcnt(0)
	v_mov_b32_e32 v99, v116
	v_mov_b32_e32 v116, v113
	v_mov_b32_e32 v98, v112
	v_pk_mul_f32 v[102:103], v[30:31], v[116:117]
	s_nop 0
	v_pk_fma_f32 v[98:99], v[28:29], v[98:99], v[102:103]
	v_mov_b32_e32 v102, v114
	v_mov_b32_e32 v103, v118
	v_pk_fma_f32 v[98:99], v[32:33], v[102:103], v[98:99]
	v_mov_b32_e32 v118, v115
	v_pk_fma_f32 v[98:99], v[34:35], v[118:119], v[98:99]
	s_nop 0
	v_add_f32_e32 v98, v104, v98
	v_add_f32_e32 v98, v98, v99
	v_min_f32_e32 v99, 0, v98
	v_mul_f32_e64 v98, |v98|, s89
	v_exp_f32_e32 v98, v98
	s_nop 0
	v_add_f32_e32 v98, 1.0, v98
	v_cmp_gt_f32_e32 vcc, s90, v98
	s_nop 1
	v_cndmask_b32_e64 v102, 0, 32, vcc
	v_ldexp_f32 v98, v98, v102
	v_log_f32_e32 v98, v98
	s_nop 0
	v_mul_f32_e32 v102, 0x3f317217, v98
	v_fma_f32 v102, v98, s91, -v102
	v_fmac_f32_e32 v102, 0x3377d1cf, v98
	v_fmac_f32_e32 v102, 0x3f317217, v98
	v_cmp_lt_f32_e64 s[44:45], |v98|, s92
	s_nop 1
	v_cndmask_b32_e64 v98, v98, v102, s[44:45]
	v_cndmask_b32_e32 v102, 0, v245, vcc
	v_sub_f32_e32 v98, v98, v102
	v_sub_f32_e32 v98, v99, v98
	v_fmac_f32_e32 v95, 0x3d800000, v98
	v_add_co_u32_e32 v98, vcc, s77, v2
	v_mul_f32_e32 v107, 0x3fb8aa3b, v95
	s_nop 0
	v_addc_co_u32_e32 v99, vcc, 0, v3, vcc
	v_add_co_u32_e32 v102, vcc, s2, v2
	v_exp_f32_e32 v107, v107
	s_nop 0
	v_addc_co_u32_e32 v103, vcc, 0, v3, vcc
	s_nop 0
	s_mov_b32 s2, 0x10001000
	s_nop 0
	v_lshlrev_b32_e32 v105, 16, v214
	s_nop 0
	v_mul_f32_e32 v105, 0x3db504f3, v105
	v_mul_f32_e32 v105, v105, v107
	v_cvt_pk_bf16_f32 v105, v105, s0
	global_store_short v[124:125], v105, off offset:2048
	v_mul_f32_e32 v105, 0xbfb8aa3b, v95
	v_exp_f32_e32 v105, v105
	ds_read_b128 v[108:111], v106 offset:192
	ds_read_b128 v[112:115], v106 offset:208
	ds_read_b128 v[116:119], v106 offset:224
	ds_read_b128 v[120:123], v106 offset:240
	v_sub_f32_e32 v107, v93, v95
	s_waitcnt lgkmcnt(3)
	v_mov_b32_e32 v130, v108
	s_waitcnt lgkmcnt(2)
	v_mov_b32_e32 v131, v112
	v_mov_b32_e32 v112, v109
	v_pk_mul_f32 v[108:109], v[22:23], v[112:113]
	v_mov_b32_e32 v112, v110
	v_pk_fma_f32 v[108:109], v[20:21], v[130:131], v[108:109]
	v_mov_b32_e32 v113, v114
	v_pk_fma_f32 v[108:109], v[24:25], v[112:113], v[108:109]
	v_mov_b32_e32 v114, v111
	v_mul_f32_e32 v107, 0x3fb8aa3b, v107
	v_pk_fma_f32 v[108:109], v[26:27], v[114:115], v[108:109]
	v_exp_f32_e32 v128, v107
	v_add_f32_e32 v107, v37, v108
	v_add_f32_e32 v107, v107, v109
	s_waitcnt lgkmcnt(0)
	v_mov_b32_e32 v109, v120
	v_mov_b32_e32 v120, v117
	v_mov_b32_e32 v108, v116
	v_pk_mul_f32 v[110:111], v[30:31], v[120:121]
	s_nop 0
	v_lshlrev_b32_e32 v104, 16, v215
	v_mul_f32_e32 v105, v105, v104
	v_cvt_pk_bf16_f32 v105, v105, s0
	global_store_short v[126:127], v105, off offset:2048
	s_nop 0
	v_pk_fma_f32 v[108:109], v[28:29], v[108:109], v[110:111]
	s_nop 0
	v_mov_b32_e32 v110, v118
	v_mov_b32_e32 v111, v122
	v_pk_fma_f32 v[108:109], v[32:33], v[110:111], v[108:109]
	v_mov_b32_e32 v122, v119
	v_pk_fma_f32 v[108:109], v[34:35], v[122:123], v[108:109]
	s_nop 0
	v_add_f32_e32 v107, v107, v108
	v_add_f32_e32 v107, v107, v109
	v_min_f32_e32 v108, 0, v107
	v_mul_f32_e64 v107, |v107|, s89
	v_exp_f32_e32 v107, v107
	s_nop 0
	v_add_f32_e32 v107, 1.0, v107
	v_cmp_gt_f32_e32 vcc, s90, v107
	s_nop 1
	v_cndmask_b32_e64 v109, 0, 32, vcc
	v_ldexp_f32 v107, v107, v109
	v_log_f32_e32 v107, v107
	s_nop 0
	v_mul_f32_e32 v109, 0x3f317217, v107
	v_fma_f32 v109, v107, s91, -v109
	v_fmac_f32_e32 v109, 0x3377d1cf, v107
	v_fmac_f32_e32 v109, 0x3f317217, v107
	v_cmp_lt_f32_e64 s[44:45], |v107|, s92
	s_nop 1
	v_cndmask_b32_e64 v107, v107, v109, s[44:45]
	v_cndmask_b32_e32 v109, 0, v245, vcc
	v_sub_f32_e32 v107, v107, v109
	v_sub_f32_e32 v107, v108, v107
	v_fmac_f32_e32 v95, 0x3d800000, v107
	v_mul_f32_e32 v107, 0x3fb8aa3b, v95
	v_exp_f32_e32 v107, v107
	v_sub_f32_e32 v109, v93, v95
	v_mul_f32_e32 v108, 0xbfb8aa3b, v95
	v_mul_f32_e32 v109, 0x3fb8aa3b, v109
	v_exp_f32_e32 v108, v108
	v_exp_f32_e32 v129, v109
	s_nop 0
	v_lshlrev_b32_e32 v109, 16, v216
	s_nop 0
	v_lshlrev_b32_e32 v105, 16, v217
	v_mul_f32_e32 v98, 0x3db504f3, v109
	v_mul_f32_e32 v98, v98, v107
	v_cvt_pk_bf16_f32 v98, v98, s0
	global_store_short v[124:125], v98, off offset:3072
	v_mul_f32_e32 v98, v108, v105
	v_cvt_pk_bf16_f32 v98, v98, s0
	global_store_short v[126:127], v98, off offset:3072
	ds_read_b128 v[108:111], v106 offset:256
	ds_read_b128 v[112:115], v106 offset:272
	ds_read_b128 v[116:119], v106 offset:288
	ds_read_b128 v[120:123], v106 offset:304
	v_pk_mul_f32 v[98:99], v[128:129], v[104:105]
	s_waitcnt lgkmcnt(3)
	v_mov_b32_e32 v104, v108
	s_waitcnt lgkmcnt(2)
	v_mov_b32_e32 v105, v112
	v_mov_b32_e32 v112, v109
	v_pk_mul_f32 v[108:109], v[22:23], v[112:113]
	s_nop 0
	v_pk_fma_f32 v[104:105], v[20:21], v[104:105], v[108:109]
	v_mov_b32_e32 v108, v110
	v_mov_b32_e32 v109, v114
	v_pk_fma_f32 v[104:105], v[24:25], v[108:109], v[104:105]
	v_mov_b32_e32 v114, v111
	v_pk_fma_f32 v[104:105], v[26:27], v[114:115], v[104:105]
	s_nop 0
	v_add_f32_e32 v104, v37, v104
	v_add_f32_e32 v107, v104, v105
	s_waitcnt lgkmcnt(0)
; #define LAS __attribute__((address_space(3)))
; DI bf16_t f2bf(float x) { return (bf16_t)(pk2(x, 0.f) & 0xffffu); }
; DI float bf2f(bf16_t v) { return __uint_as_float(((unsigned)v) << 16); }
; DI float logsig(float z) { return fminf(z, 0.f) - __logf(1.f + __expf(-fabsf(z))); }
; DI void gla_gate_phase(int wv, LAS unsigned char* lds, const float* x, const float* w_in, const float* w2, const float* bg, const bf16_t* qk1,
;                        bf16_t* qd, bf16_t* ki, bf16_t* kst, float* decay, bf16_t* sbuf) {
;     ...
;             for (int u = 0; u < 8; ++u) { const int t = t8 + u; float z = bc;
; #pragma unroll
;                 for (int q = 0; q < 4; ++q) { const f32x4 gv = *(const LAS f32x4*)(gl + t * 16 + 4 * q); z += gv.x * w2c[4 * q] + gv.y * w2c[4 * q + 1] + gv.z * w2c[4 * q + 2] + gv.w * w2c[4 * q + 3]; }
;                 cum += logsig(z) * 0.0625f;
;                 const size_t tok = T0 + t;
;                 const float qv = bf2f(qk1[tok * 1024 + c]), kv = bf2f(qk1[tok * 1024 + 512 + c]);
;                 qd[tok * 512 + c] = f2bf(qv * 0.08838834764831845f * __expf(cum));
;                 ki[tok * 512 + c] = f2bf(kv * __expf(-cum));
;                 ksv[u] = kv * __expf(blast - cum); }
	v_mov_b32_e32 v105, v120
	v_mov_b32_e32 v120, v117
	v_mov_b32_e32 v104, v116
	v_pk_mul_f32 v[108:109], v[30:31], v[120:121]
	s_nop 0
	v_pk_fma_f32 v[104:105], v[28:29], v[104:105], v[108:109]
	v_mov_b32_e32 v108, v118
	v_mov_b32_e32 v109, v122
	v_pk_fma_f32 v[104:105], v[32:33], v[108:109], v[104:105]
	v_mov_b32_e32 v122, v119
	v_pk_fma_f32 v[104:105], v[34:35], v[122:123], v[104:105]
	s_nop 0
	v_add_f32_e32 v104, v107, v104
	v_add_f32_e32 v104, v104, v105
	v_min_f32_e32 v105, 0, v104
	v_mul_f32_e64 v104, |v104|, s89
	v_exp_f32_e32 v104, v104
	s_nop 0
	v_add_f32_e32 v104, 1.0, v104
	v_cmp_gt_f32_e32 vcc, s90, v104
	s_nop 1
	v_cndmask_b32_e64 v107, 0, 32, vcc
	v_ldexp_f32 v104, v104, v107
	v_log_f32_e32 v104, v104
	s_nop 0
	v_mul_f32_e32 v107, 0x3f317217, v104
	v_fma_f32 v107, v104, s91, -v107
	v_fmac_f32_e32 v107, 0x3377d1cf, v104
	v_fmac_f32_e32 v107, 0x3f317217, v104
	v_cmp_lt_f32_e64 s[44:45], |v104|, s92
	s_nop 1
	v_cndmask_b32_e64 v104, v104, v107, s[44:45]
	v_cndmask_b32_e32 v107, 0, v245, vcc
	v_sub_f32_e32 v104, v104, v107
	v_sub_f32_e32 v104, v105, v104
	v_fmac_f32_e32 v95, 0x3d800000, v104
	s_nop 0
	v_mul_f32_e32 v107, 0x3fb8aa3b, v95
	v_exp_f32_e32 v107, v107
	v_add_co_u32_e32 v100, vcc, s2, v100
	s_mov_b32 s2, 0x4001000
	s_nop 0
	v_addc_co_u32_e32 v101, vcc, 0, v101, vcc
	s_nop 0
	v_lshlrev_b32_e32 v105, 16, v218
	s_nop 0
	v_mul_f32_e32 v105, 0x3db504f3, v105
	v_mul_f32_e32 v105, v105, v107
	v_cvt_pk_bf16_f32 v105, v105, s0
	global_store_short v[100:101], v105, off
	ds_read_b128 v[108:111], v106 offset:320
	ds_read_b128 v[112:115], v106 offset:336
	ds_read_b128 v[116:119], v106 offset:352
	ds_read_b128 v[120:123], v106 offset:368
	v_sub_f32_e32 v107, v93, v95
	s_waitcnt lgkmcnt(3)
	v_mov_b32_e32 v126, v108
	s_waitcnt lgkmcnt(2)
	v_mov_b32_e32 v127, v112
	v_mov_b32_e32 v112, v109
	v_pk_mul_f32 v[108:109], v[22:23], v[112:113]
	v_mov_b32_e32 v112, v110
	v_pk_fma_f32 v[108:109], v[20:21], v[126:127], v[108:109]
	v_mov_b32_e32 v113, v114
	v_pk_fma_f32 v[108:109], v[24:25], v[112:113], v[108:109]
	v_mov_b32_e32 v114, v111
	v_mul_f32_e32 v107, 0x3fb8aa3b, v107
	v_pk_fma_f32 v[108:109], v[26:27], v[114:115], v[108:109]
	v_exp_f32_e32 v124, v107
	v_add_f32_e32 v107, v37, v108
	v_add_f32_e32 v107, v107, v109
	s_waitcnt lgkmcnt(0)
	v_mov_b32_e32 v109, v120
	v_mov_b32_e32 v120, v117
	v_mov_b32_e32 v108, v116
	v_pk_mul_f32 v[110:111], v[30:31], v[120:121]
	v_mul_f32_e32 v105, 0xbfb8aa3b, v95
	v_pk_fma_f32 v[108:109], v[28:29], v[108:109], v[110:111]
	v_mov_b32_e32 v110, v118
	v_mov_b32_e32 v111, v122
	v_pk_fma_f32 v[108:109], v[32:33], v[110:111], v[108:109]
	v_mov_b32_e32 v122, v119
	v_pk_fma_f32 v[108:109], v[34:35], v[122:123], v[108:109]
	v_exp_f32_e32 v105, v105
	v_add_f32_e32 v107, v107, v108
	v_add_f32_e32 v107, v107, v109
	v_min_f32_e32 v108, 0, v107
	v_mul_f32_e64 v107, |v107|, s89
	v_exp_f32_e32 v107, v107
	s_nop 0
	v_lshlrev_b32_e32 v104, 16, v219
	v_add_f32_e32 v107, 1.0, v107
	v_cmp_gt_f32_e32 vcc, s90, v107
	v_mul_f32_e32 v105, v105, v104
	v_cvt_pk_bf16_f32 v105, v105, s0
	v_cndmask_b32_e64 v109, 0, 32, vcc
	v_ldexp_f32 v107, v107, v109
	v_log_f32_e32 v107, v107
	s_nop 0
	v_mul_f32_e32 v109, 0x3f317217, v107
	v_fma_f32 v109, v107, s91, -v109
	v_fmac_f32_e32 v109, 0x3377d1cf, v107
	v_fmac_f32_e32 v109, 0x3f317217, v107
	v_cmp_lt_f32_e64 s[44:45], |v107|, s92
	s_nop 1
	v_cndmask_b32_e64 v107, v107, v109, s[44:45]
	v_cndmask_b32_e32 v109, 0, v245, vcc
	v_add_co_u32_e32 v96, vcc, s2, v96
	v_sub_f32_e32 v107, v107, v109
	s_nop 0
	v_addc_co_u32_e32 v97, vcc, 0, v97, vcc
	global_store_short v[96:97], v105, off
	s_nop 0
	v_sub_f32_e32 v107, v108, v107
	s_nop 0
	v_fmac_f32_e32 v95, 0x3d800000, v107
	v_mul_f32_e32 v107, 0x3fb8aa3b, v95
	v_exp_f32_e32 v107, v107
	v_sub_f32_e32 v109, v93, v95
	v_mul_f32_e32 v108, 0xbfb8aa3b, v95
	v_mul_f32_e32 v109, 0x3fb8aa3b, v109
	v_exp_f32_e32 v108, v108
	v_exp_f32_e32 v125, v109
	s_nop 0
	v_lshlrev_b32_e32 v109, 16, v220
	s_nop 0
	v_lshlrev_b32_e32 v105, 16, v221
	v_mul_f32_e32 v102, 0x3db504f3, v109
	v_mul_f32_e32 v102, v102, v107
	v_cvt_pk_bf16_f32 v102, v102, s0
	global_store_short v[100:101], v102, off offset:1024
	v_mul_f32_e32 v102, v108, v105
	v_cvt_pk_bf16_f32 v102, v102, s0
	global_store_short v[96:97], v102, off offset:1024
	v_pk_mul_f32 v[120:121], v[124:125], v[104:105]
	ds_read_b128 v[102:105], v106 offset:384
	ds_read_b128 v[108:111], v106 offset:400
	ds_read_b128 v[112:115], v106 offset:416
	ds_read_b128 v[116:119], v106 offset:432
	s_waitcnt lgkmcnt(3)
	v_mov_b32_e32 v122, v102
	s_waitcnt lgkmcnt(2)
	v_mov_b32_e32 v123, v108
	v_mov_b32_e32 v108, v103
	v_pk_mul_f32 v[102:103], v[22:23], v[108:109]
	v_mov_b32_e32 v108, v104
	v_pk_fma_f32 v[102:103], v[20:21], v[122:123], v[102:103]
	v_mov_b32_e32 v109, v110
	v_pk_fma_f32 v[102:103], v[24:25], v[108:109], v[102:103]
	v_mov_b32_e32 v110, v105
	v_pk_fma_f32 v[102:103], v[26:27], v[110:111], v[102:103]
	s_nop 0
	v_add_f32_e32 v102, v37, v102
	v_add_f32_e32 v107, v102, v103
	s_waitcnt lgkmcnt(0)
; #define LAS __attribute__((address_space(3)))
; DI unsigned pk2(float lo, float hi) { f32x2 f = {lo, hi}; bf2_t v = __builtin_convertvector(f, bf2_t); return __builtin_bit_cast(unsigned, v); }
; DI bf16_t f2bf(float x) { return (bf16_t)(pk2(x, 0.f) & 0xffffu); }
; DI float bf2f(bf16_t v) { return __uint_as_float(((unsigned)v) << 16); }
; #define MFMA32(a, b, c) __builtin_amdgcn_mfma_f32_32x32x16_bf16((a), (b), (c), 0, 0, 0)
; DI f32x16 zero16() { f32x16 z; for (int i = 0; i < 16; ++i) z[i] = 0.f; return z; }
; DI float logsig(float z) { return fminf(z, 0.f) - __logf(1.f + __expf(-fabsf(z))); }
; DI void gla_gate_phase(int wv, LAS unsigned char* lds, const float* x, const float* w_in, const float* w2, const float* bg, const bf16_t* qk1,
;                        bf16_t* qd, bf16_t* ki, bf16_t* kst, float* decay, bf16_t* sbuf) {
;     ...
;             for (int u = 0; u < 8; ++u) { const int t = t8 + u; float z = bc;
; #pragma unroll
;                 for (int q = 0; q < 4; ++q) { const f32x4 gv = *(const LAS f32x4*)(gl + t * 16 + 4 * q); z += gv.x * w2c[4 * q] + gv.y * w2c[4 * q + 1] + gv.z * w2c[4 * q + 2] + gv.w * w2c[4 * q + 3]; }
;                 cum += logsig(z) * 0.0625f;
;                 const size_t tok = T0 + t;
;                 const float qv = bf2f(qk1[tok * 1024 + c]), kv = bf2f(qk1[tok * 1024 + 512 + c]);
;                 qd[tok * 512 + c] = f2bf(qv * 0.08838834764831845f * __expf(cum));
;                 ki[tok * 512 + c] = f2bf(kv * __expf(-cum));
;                 ksv[u] = kv * __expf(blast - cum); }
;             u32x4 w; w.x = pk2(ksv[0], ksv[1]); w.y = pk2(ksv[2], ksv[3]); w.z = pk2(ksv[4], ksv[5]); w.w = pk2(ksv[6], ksv[7]);
;             *(u32x4*)(kst + ((size_t)b * 512 + c) * SEQ + ch * 64 + t8) = w;
;         }
;         __syncthreads();
;         const int hd = wid >> 1;
; #pragma unroll
;         for (int u = 0; u < 2; ++u) {
;             const int tt2 = (wid & 1) * 2 + u, kt = tt2 >> 1, qt = tt2 & 1;
;             f32x16 S = zero16();
;             if (!(kt == 1 && qt == 0)) {
; #pragma unroll
;                 for (int ks = 0; ks < 8; ++ks) { const bf16x8 A = *(const bf16x8*)(ki + (T0 + kt * 32 + rr) * 512 + hd * 128 + ks * 16 + hh * 8);
;                     const bf16x8 B = *(const bf16x8*)(qd + (T0 + qt * 32 + rr) * 512 + hd * 128 + ks * 16 + hh * 8); S = MFMA32(A, B, S); } }
	v_mov_b32_e32 v103, v116
	v_mov_b32_e32 v116, v113
	v_mov_b32_e32 v102, v112
	v_pk_mul_f32 v[104:105], v[30:31], v[116:117]
	s_nop 0
	v_pk_fma_f32 v[102:103], v[28:29], v[102:103], v[104:105]
	v_mov_b32_e32 v104, v114
	v_mov_b32_e32 v105, v118
	v_pk_fma_f32 v[102:103], v[32:33], v[104:105], v[102:103]
	v_mov_b32_e32 v118, v115
	v_pk_fma_f32 v[102:103], v[34:35], v[118:119], v[102:103]
	s_nop 0
	v_add_f32_e32 v102, v107, v102
	v_add_f32_e32 v102, v102, v103
	v_min_f32_e32 v103, 0, v102
	v_mul_f32_e64 v102, |v102|, s89
	v_exp_f32_e32 v102, v102
	s_nop 0
	v_add_f32_e32 v102, 1.0, v102
	v_cmp_gt_f32_e32 vcc, s90, v102
	s_nop 1
	v_cndmask_b32_e64 v104, 0, 32, vcc
	v_ldexp_f32 v102, v102, v104
	v_log_f32_e32 v102, v102
	s_nop 0
	v_mul_f32_e32 v104, 0x3f317217, v102
	v_fma_f32 v104, v102, s91, -v104
	v_fmac_f32_e32 v104, 0x3377d1cf, v102
	v_fmac_f32_e32 v104, 0x3f317217, v102
	v_cmp_lt_f32_e64 s[44:45], |v102|, s92
	s_nop 1
	v_cndmask_b32_e64 v102, v102, v104, s[44:45]
	v_cndmask_b32_e32 v104, 0, v245, vcc
	v_sub_f32_e32 v102, v102, v104
	v_add_co_u32_e32 v2, vcc, s88, v2
	v_sub_f32_e32 v102, v103, v102
	s_nop 0
	v_addc_co_u32_e32 v3, vcc, 0, v3, vcc
	v_fmac_f32_e32 v95, 0x3d800000, v102
	s_nop 0
	s_nop 0
	s_nop 0
	v_lshlrev_b32_e32 v102, 16, v222
	s_nop 0
	v_lshlrev_b32_e32 v122, 16, v223
	v_mul_f32_e32 v103, 0x3fb8aa3b, v95
	v_exp_f32_e32 v103, v103
	v_mul_f32_e32 v102, 0x3db504f3, v102
	v_mul_f32_e32 v102, v102, v103
	v_cvt_pk_bf16_f32 v102, v102, s0
	global_store_short v[100:101], v102, off offset:2048
	v_mul_f32_e32 v102, 0xbfb8aa3b, v95
	v_exp_f32_e32 v123, v102
	v_sub_f32_e32 v102, v93, v95
	v_mul_f32_e32 v102, 0x3fb8aa3b, v102
	v_exp_f32_e32 v124, v102
	ds_read_b128 v[102:105], v106 offset:448
	ds_read_b128 v[108:111], v106 offset:464
	ds_read_b128 v[112:115], v106 offset:480
	ds_read_b128 v[116:119], v106 offset:496
	s_waitcnt lgkmcnt(3)
	v_mov_b32_e32 v106, v102
	s_waitcnt lgkmcnt(2)
	v_mov_b32_e32 v107, v108
	v_mov_b32_e32 v108, v103
	v_pk_mul_f32 v[102:103], v[22:23], v[108:109]
	s_nop 0
	v_pk_fma_f32 v[102:103], v[20:21], v[106:107], v[102:103]
	v_mov_b32_e32 v106, v104
	v_mov_b32_e32 v107, v110
	v_pk_fma_f32 v[102:103], v[24:25], v[106:107], v[102:103]
	v_mov_b32_e32 v110, v105
	v_pk_fma_f32 v[102:103], v[26:27], v[110:111], v[102:103]
	s_nop 0
	v_add_f32_e32 v102, v37, v102
	v_add_f32_e32 v106, v102, v103
	s_waitcnt lgkmcnt(0)
	v_mov_b32_e32 v103, v116
	v_mov_b32_e32 v116, v113
	v_mov_b32_e32 v102, v112
	v_pk_mul_f32 v[104:105], v[30:31], v[116:117]
	s_nop 0
	v_pk_fma_f32 v[102:103], v[28:29], v[102:103], v[104:105]
	v_mov_b32_e32 v104, v114
	v_mov_b32_e32 v105, v118
	v_pk_fma_f32 v[102:103], v[32:33], v[104:105], v[102:103]
	v_mov_b32_e32 v118, v115
	v_pk_fma_f32 v[102:103], v[34:35], v[118:119], v[102:103]
	s_nop 0
	v_add_f32_e32 v102, v106, v102
	v_add_f32_e32 v102, v102, v103
	v_min_f32_e32 v103, 0, v102
	v_mul_f32_e64 v102, |v102|, s89
	v_exp_f32_e32 v102, v102
	s_nop 0
	v_add_f32_e32 v102, 1.0, v102
	v_cmp_gt_f32_e32 vcc, s90, v102
	s_nop 1
	v_cndmask_b32_e64 v104, 0, 32, vcc
	v_ldexp_f32 v102, v102, v104
	v_log_f32_e32 v102, v102
	s_nop 0
	v_mul_f32_e32 v104, 0x3f317217, v102
	v_fma_f32 v104, v102, s91, -v104
	v_fmac_f32_e32 v104, 0x3377d1cf, v102
	v_fmac_f32_e32 v104, 0x3f317217, v102
	v_cmp_lt_f32_e64 s[44:45], |v102|, s92
	s_nop 1
	v_cndmask_b32_e64 v102, v102, v104, s[44:45]
	v_cndmask_b32_e32 v104, 0, v245, vcc
	v_sub_f32_e32 v102, v102, v104
	v_sub_f32_e32 v102, v103, v102
	v_fmac_f32_e32 v95, 0x3d800000, v102
	v_sub_f32_e32 v104, v93, v95
	v_mul_f32_e32 v104, 0x3fb8aa3b, v104
	v_exp_f32_e32 v125, v104
	v_mul_f32_e32 v104, v123, v122
	v_cvt_pk_bf16_f32 v104, v104, s0
	global_store_short v[96:97], v104, off offset:2048
	s_nop 0
	v_mul_f32_e32 v102, 0x3fb8aa3b, v95
	s_nop 0
	v_exp_f32_e32 v102, v102
	v_mul_f32_e32 v103, 0xbfb8aa3b, v95
	v_exp_f32_e32 v103, v103
	v_cvt_pk_bf16_f32 v3, v98, v99
	s_nop 0
	v_lshlrev_b32_e32 v104, 16, v224
	s_nop 0
	v_lshlrev_b32_e32 v123, 16, v225
	v_mul_f32_e32 v2, 0x3db504f3, v104
	v_mul_f32_e32 v2, v2, v102
	v_cvt_pk_bf16_f32 v2, v2, s0
	global_store_short v[100:101], v2, off offset:3072
	v_mul_f32_e32 v2, v103, v123
	v_cvt_pk_bf16_f32 v2, v2, s0
	global_store_short v[96:97], v2, off offset:3072
	v_pk_mul_f32 v[96:97], v[124:125], v[122:123]
	v_cvt_pk_bf16_f32 v2, v4, v5
	v_cvt_pk_bf16_f32 v4, v120, v121
	v_cvt_pk_bf16_f32 v5, v96, v97
	v_lshl_add_u64 v[96:97], s[48:49], 0, v[16:17]
	v_lshl_add_u64 v[16:17], v[16:17], 0, 16
	global_store_dwordx4 v[96:97], v[2:5], off
	s_cbranch_scc0 .LBB0_148
	s_lshl_b32 s1, s0, 6
	s_or_b32 s1, s86, s1
	v_mov_b32_e32 v3, s87
	v_or_b32_e32 v2, s1, v48
	v_lshlrev_b64 v[2:3], 10, v[2:3]
	v_lshl_add_u64 v[96:97], v[44:45], 0, v[2:3]
	v_mov_b32_e32 v3, s87
	v_or_b32_e32 v2, s1, v36
	v_lshlrev_b64 v[4:5], 10, v[2:3]
	v_readlane_b32 s2, v254, 36
	v_mov_b32_e32 v2, 0
	v_lshl_add_u64 v[98:99], v[46:47], 0, v[4:5]
	v_mov_b32_e32 v3, 0
	v_mov_b32_e32 v4, 0
	v_mov_b32_e32 v5, 0
	v_mov_b32_e32 v6, 0
	v_mov_b32_e32 v7, 0
	v_mov_b32_e32 v8, 0
	v_mov_b32_e32 v9, 0
	v_mov_b32_e32 v10, 0
	v_mov_b32_e32 v11, 0
	v_mov_b32_e32 v12, 0
	v_mov_b32_e32 v13, 0
	v_mov_b32_e32 v14, 0
	v_mov_b32_e32 v15, 0
	v_mov_b32_e32 v16, 0
	v_mov_b32_e32 v17, 0
	v_readlane_b32 s3, v254, 37
	s_barrier
	s_and_saveexec_b64 s[44:45], s[2:3]
	s_cbranch_execz .LBB0_140
	global_load_dwordx4 v[2:5], v[96:97], off
	global_load_dwordx4 v[6:9], v[98:99], off
	global_load_dwordx4 v[100:103], v[96:97], off offset:32
	global_load_dwordx4 v[104:107], v[98:99], off offset:32
	global_load_dwordx4 v[136:139], v[96:97], off offset:64
	global_load_dwordx4 v[140:143], v[98:99], off offset:64
	global_load_dwordx4 v[144:147], v[96:97], off offset:96
	global_load_dwordx4 v[148:151], v[98:99], off offset:96
	global_load_dwordx4 v[152:155], v[96:97], off offset:128
	global_load_dwordx4 v[156:159], v[98:99], off offset:128
	global_load_dwordx4 v[160:163], v[96:97], off offset:160
	global_load_dwordx4 v[216:219], v[98:99], off offset:160
	global_load_dwordx4 v[220:223], v[96:97], off offset:192
	global_load_dwordx4 v[224:227], v[98:99], off offset:192
	global_load_dwordx4 v[176:179], v[96:97], off offset:224
	global_load_dwordx4 v[180:183], v[98:99], off offset:224
	s_waitcnt vmcnt(14)
	v_mfma_f32_32x32x16_bf16 v[2:17], v[2:5], v[6:9], 0
	s_waitcnt vmcnt(12)
	v_mfma_f32_32x32x16_bf16 v[2:17], v[100:103], v[104:107], v[2:17]
	s_waitcnt vmcnt(10)
	v_mfma_f32_32x32x16_bf16 v[2:17], v[136:139], v[140:143], v[2:17]
	s_waitcnt vmcnt(8)
	v_mfma_f32_32x32x16_bf16 v[2:17], v[144:147], v[148:151], v[2:17]
	s_waitcnt vmcnt(6)
	v_mfma_f32_32x32x16_bf16 v[2:17], v[152:155], v[156:159], v[2:17]
	s_waitcnt vmcnt(4)
	v_mfma_f32_32x32x16_bf16 v[2:17], v[160:163], v[216:219], v[2:17]
	s_waitcnt vmcnt(2)
	v_mfma_f32_32x32x16_bf16 v[2:17], v[220:223], v[224:227], v[2:17]
	s_waitcnt vmcnt(0)
	v_mfma_f32_32x32x16_bf16 v[2:17], v[176:179], v[180:183], v[2:17]
	s_branch .LBB0_140

; #define LAS __attribute__((address_space(3)))
; DI f32x16 zero16() { f32x16 z; for (int i = 0; i < 16; ++i) z[i] = 0.f; return z; }
; DI void diff_attn_phase(int wv, LAS unsigned char* lds, const bf16_t* qk, const bf16_t* vt, bf16_t* ob, const float* lq1, const float* lk1, const float* lq2, const float* lk2,
;                         const float* subg, int layer_idx) {
;     ...
;         const int rho = it >> 8, j = it & 255, grp = j >> 6, bh = j & 63;
;         const int qb = 28 - 4 * rho + ((rho & 1) ? grp : 3 - grp);
;         const int b = bh >> 3, hd = bh & 7;
;         const int q0 = qb * 128 + qsub * 32, nkt = 2 * qb + 2, qpos = q0 + rr;
;         const float slope2 = exp2f(-(float)(hd + 1)) * LOG2E;
;         const bf16_t* qkb = qk + (size_t)b * SEQ * 2048;
;         LAS unsigned char* qlds = lds + 2 * DA_BUF + wid * 4096 + lane * 16;
; #pragma unroll
;         for (int ks = 0; ks < 4; ++ks) *(LAS bf16x8*)(qlds + ks * 1024) = *(const bf16x8*)(qkb + (size_t)(q0 + rr) * 2048 + hd * 128 + map * 64 + ks * 16 + hh * 8);
;         const bf16_t* kg = qkb + 1024 + hd * 128 + kch * 8 + (size_t)krow0 * 2048;
;         const bf16_t* vg = vt + (size_t)(hd * 128 + vrow0) * M_TOK + (size_t)b * SEQ + vch * 8;
;         float cb[16];
; #pragma unroll
;         for (int i = 0; i < 16; ++i) cb[i] = slope2 * (float)((i & 7) + 16 * (i >> 3));
;         f32x16 O[4];
; #pragma unroll
;         for (int d = 0; d < 4; ++d) O[d] = zero16();
;         float m = -INFINITY, l = 0.f;
;         if (!have_pf) {
; #pragma unroll
;             for (int i = 0; i < 2; ++i) { gk[i] = *(const u32x4*)(kg + (size_t)i * 32 * 2048); gv[i] = *(const u32x4*)(vg + (size_t)i * 64 * M_TOK); } }
; #pragma unroll
;         for (int i = 0; i < 2; ++i) { *(LAS u32x4*)(lds + kst_off + i * 32 * DA_KP) = gk[i]; *(LAS u32x4*)(lds + vst_off + i * 64 * DA_VP) = gv[i]; }
.LBB0_420:
	s_bfe_u32 s0, s18, 0x20006
	s_ashr_i32 s1, s18, 6
	s_and_b32 s2, s1, -4
	s_and_b32 s3, s18, 0x100
	s_xor_b32 s14, s0, 3
	s_cmp_eq_u32 s3, 0
	s_cselect_b32 s14, s14, s0
	s_sub_i32 s15, s14, s2
	s_add_i32 s15, s15, 28
	s_lshl_b32 s2, s18, 9
	s_lshl_b32 s0, s15, 7
	s_and_b32 s23, s2, 0x7000
	s_and_b32 s16, s18, 7
	s_or_b32 s22, s0, s19
	s_lshl_b32 s2, s23, 12
	v_or_b32_e32 v162, s22, v147
	s_add_u32 s26, s72, s2
	v_mov_b32_e32 v163, v1
	s_addc_u32 s27, s73, 0
	v_lshlrev_b64 v[2:3], 12, v[162:163]
	v_lshl_add_u64 v[2:3], s[26:27], 0, v[2:3]
	s_lshl_b32 s56, s16, 8
	v_lshl_add_u64 v[2:3], v[2:3], 0, s[56:57]
	v_lshl_add_u64 v[2:3], s[4:5], 1, v[2:3]
	v_mov_b32_e32 v157, v1
	v_lshl_add_u64 v[6:7], v[2:3], 0, v[156:157]
	global_load_dwordx4 v[2:5], v[6:7], off
	global_load_dwordx4 v[8:11], v[6:7], off offset:32
	global_load_dwordx4 v[12:15], v[6:7], off offset:64
	global_load_dwordx4 v[16:19], v[6:7], off offset:96
	s_lshl_b32 s24, s16, 7
	s_add_u32 s26, s26, s56
	s_addc_u32 s27, s27, 0
	v_lshlrev_b32_e32 v164, 1, v148
	v_mov_b32_e32 v165, v1
	s_lshl_b32 s56, s23, 1
	v_lshlrev_b32_e32 v190, 1, v152
	v_mov_b32_e32 v191, v1
	s_and_b64 vcc, exec, s[12:13]
	s_waitcnt vmcnt(0)
	ds_write_b128 v217, v[2:5]
	ds_write_b128 v217, v[8:11] offset:1024
	ds_write_b128 v217, v[12:15] offset:2048
	ds_write_b128 v217, v[16:19] offset:3072
	v_add_u32_e32 v4, s24, v161
	v_ashrrev_i32_e32 v5, 31, v4
	v_lshlrev_b64 v[4:5], 16, v[4:5]
	v_lshl_add_u64 v[4:5], s[78:79], 0, v[4:5]
	v_lshl_add_u64 v[2:3], s[26:27], 0, v[164:165]
	v_lshl_add_u64 v[4:5], v[4:5], 0, s[56:57]
	v_lshl_add_u64 v[114:115], v[150:151], 1, v[2:3]
	v_lshl_add_u64 v[116:117], v[4:5], 0, v[190:191]
	s_cbranch_vccnz .LBB0_422
	v_add_co_u32_e32 v2, vcc, 0x20000, v114
	global_load_dwordx4 v[102:105], v[114:115], off offset:2048
	global_load_dwordx4 v[98:101], v[116:117], off
	v_addc_co_u32_e32 v3, vcc, 0, v115, vcc
	v_add_co_u32_e32 v4, vcc, 0x400000, v116
	s_nop 1
	v_addc_co_u32_e32 v5, vcc, 0, v117, vcc
	global_load_dwordx4 v[106:109], v[2:3], off offset:2048
	global_load_dwordx4 v[110:113], v[4:5], off
